# attention context items (last 512 work items) store bf16 rows write-through so the post-attention barrier write-back is nearly clean
# baseline (speedup 1.0000x reference)
.LBB0_308:
	v_readlane_b32 s2, v251, 52
	v_lshlrev_b64 v[46:47], 11, v[84:85]
	v_readlane_b32 s3, v251, 53
	v_pk_mul_f32 v[22:23], v[22:23], v[44:45]
	v_pk_mul_f32 v[24:25], v[24:25], v[44:45]
	v_pk_mul_f32 v[26:27], v[26:27], v[44:45]
	v_pk_mul_f32 v[28:29], v[28:29], v[44:45]
	v_pk_mul_f32 v[30:31], v[30:31], v[44:45]
	v_pk_mul_f32 v[32:33], v[32:33], v[44:45]
	v_pk_mul_f32 v[34:35], v[34:35], v[44:45]
	v_pk_mul_f32 v[6:7], v[6:7], v[44:45]
	v_pk_mul_f32 v[8:9], v[8:9], v[44:45]
	v_pk_mul_f32 v[10:11], v[10:11], v[44:45]
	v_pk_mul_f32 v[12:13], v[12:13], v[44:45]
	v_pk_mul_f32 v[14:15], v[14:15], v[44:45]
	v_pk_mul_f32 v[16:17], v[16:17], v[44:45]
	v_pk_mul_f32 v[18:19], v[18:19], v[44:45]
	v_lshl_add_u64 v[46:47], s[2:3], 0, v[46:47]
	v_cvt_pk_bf16_f32 v48, v40, v41
	v_cvt_pk_bf16_f32 v49, v22, v23
	v_cvt_pk_bf16_f32 v50, v24, v25
	v_cvt_pk_bf16_f32 v51, v26, v27
	v_cvt_pk_bf16_f32 v52, v28, v29
	v_cvt_pk_bf16_f32 v53, v30, v31
	v_cvt_pk_bf16_f32 v54, v32, v33
	v_cvt_pk_bf16_f32 v55, v34, v35
	v_cvt_pk_bf16_f32 v56, v36, v37
	v_cvt_pk_bf16_f32 v57, v6, v7
	v_cvt_pk_bf16_f32 v58, v8, v9
	v_cvt_pk_bf16_f32 v59, v10, v11
	v_cvt_pk_bf16_f32 v60, v12, v13
	v_cvt_pk_bf16_f32 v61, v14, v15
	v_cvt_pk_bf16_f32 v62, v16, v17
	v_cvt_pk_bf16_f32 v63, v18, v19
	v_lshl_add_u64 v[46:47], v[2:3], 2, v[46:47]
	s_nop 1
	v_permlane32_swap_b32 v48, v50
	v_permlane32_swap_b32 v49, v51
	v_permlane32_swap_b32 v52, v54
	v_permlane32_swap_b32 v53, v55
	v_permlane32_swap_b32 v56, v58
	v_permlane32_swap_b32 v57, v59
	v_permlane32_swap_b32 v60, v62
	v_permlane32_swap_b32 v61, v63
	s_nop 1
	s_cmp_lg_u32 s101, 0
	s_cbranch_scc1 .Lst_wt_64
	global_store_dwordx4 v[46:47], v[48:51], off
	global_store_dwordx4 v[46:47], v[52:55], off offset:32
	global_store_dwordx4 v[46:47], v[56:59], off offset:64
	global_store_dwordx4 v[46:47], v[60:63], off offset:96
	s_branch .Lst_done_64
.Lst_wt_64:
	global_store_dwordx4 v[46:47], v[48:51], off sc1
	global_store_dwordx4 v[46:47], v[52:55], off offset:32 sc1
	global_store_dwordx4 v[46:47], v[56:59], off offset:64 sc1
	global_store_dwordx4 v[46:47], v[60:63], off offset:96 sc1
.Lst_done_64:
.LBB0_309:
	s_barrier

.LBB0_316:
	s_or_b64 exec, exec, s[2:3]
	s_waitcnt lgkmcnt(0)
	s_barrier
	ds_read_b32 v2, v188
	s_mov_b64 s[2:3], -1
	s_waitcnt lgkmcnt(0)
	v_readfirstlane_b32 s39, v2
	s_cmpk_gt_i32 s39, 0x43f
	s_cbranch_scc1 .LBB0_311
	s_cmpk_ge_i32 s39, 0x240
	s_cselect_b32 s101, 1, 0
	s_cmpk_lt_i32 s39, 0x80
	s_cselect_b64 s[2:3], -1, 0
	s_cmpk_gt_i32 s39, 0x7f
	s_mov_b64 s[4:5], -1
	s_cbranch_scc1 .LBB0_319
	s_ashr_i32 s0, s39, 6
	s_lshl_b32 s6, s0, 8
	s_lshl_b32 s4, s0, 12
	s_lshl_b32 s5, s39, 8
	s_add_i32 s8, s6, 0x4000
	s_addk_i32 s4, 0x2000
	s_and_b32 s36, s5, 0xf00
	s_ashr_i32 s9, s8, 31
	s_bfe_u32 s18, s39, 0x20004
	s_or_b32 s16, s4, s36
	s_lshl_b64 s[10:11], s[8:9], 9
	v_readlane_b32 s20, v253, 44
	v_readlane_b32 s21, v253, 45
	s_add_u32 s0, s20, s10
	s_addc_u32 s5, s21, s11
	s_lshl_b32 s19, s18, 7
	s_add_u32 s12, s0, s19
	s_addc_u32 s13, s5, 0
	s_lshl_b64 s[8:9], s[8:9], 6
	v_readlane_b32 s22, v253, 48
	v_readlane_b32 s23, v253, 49
	s_add_u32 s26, s22, s8
	s_addc_u32 s27, s23, s9
	s_mul_i32 s0, s18, 0x210000
	v_readlane_b32 s8, v253, 46
	v_readlane_b32 s9, v253, 47
	s_add_u32 s0, s8, s0
	s_addc_u32 s10, s9, 0
	s_ashr_i32 s7, s6, 31
	s_lshl_b64 s[6:7], s[6:7], 1
	s_add_u32 s5, s0, s6
	s_addc_u32 s6, s10, s7
	s_add_u32 s14, s5, 0x8000
	s_addc_u32 s15, s6, 0
	s_ashr_i32 s5, s4, 31
	s_lshl_b64 s[6:7], s[4:5], 9
	s_add_u32 s6, s20, s6
	s_addc_u32 s7, s21, s7
	s_add_u32 s6, s6, s19
	s_addc_u32 s7, s7, 0
	s_lshl_b64 s[8:9], s[4:5], 6
	s_add_u32 s24, s22, s8
	s_addc_u32 s25, s23, s9
	s_lshl_b64 s[4:5], s[4:5], 1
	s_add_u32 s8, s0, s4
	s_addc_u32 s9, s10, s5
	s_ashr_i32 s17, s16, 31
	s_mul_i32 s4, s16, 0x300
	v_readlane_b32 s10, v253, 42
	s_mul_hi_i32 s0, s16, 0x300
	v_readlane_b32 s11, v253, 43
	s_add_u32 s4, s10, s4
	s_addc_u32 s0, s11, s0
	s_mulk_i32 s18, 0xc0
	s_add_u32 s10, s4, s18
	s_addc_u32 s11, s0, 0
	s_lshl_b64 s[4:5], s[16:17], 11
	v_readlane_b32 s0, v251, 32
	s_add_u32 s0, s0, s4
	v_readlane_b32 s4, v251, 33
	s_addc_u32 s4, s4, s5
	s_add_u32 s0, s0, s19
	s_addc_u32 s4, s4, 0
	s_add_u32 s16, s0, 0x300
	s_addc_u32 s17, s4, 0
	v_writelane_b32 v251, s16, 52
	s_mov_b64 s[4:5], 0
	s_nop 0
	v_writelane_b32 v251, s17, 53

.LBB0_386:
	v_xor_b32_e32 v2, 32, v229
	v_cmp_lt_i32_e32 vcc, v2, v231
	v_mov_b32_e32 v99, v3
	s_waitcnt vmcnt(0) lgkmcnt(0)
	v_cndmask_b32_e32 v2, v229, v2, vcc
	v_lshlrev_b32_e32 v2, 2, v2
	ds_bpermute_b32 v2, v2, v36
	s_barrier
	s_waitcnt lgkmcnt(0)
	s_mov_b64 s[28:29], 0
	v_add_f32_e32 v2, v36, v2
	v_div_scale_f32 v36, s[2:3], v2, v2, 1.0
	v_rcp_f32_e32 v37, v36
	v_div_scale_f32 v38, vcc, 1.0, v2, 1.0
	v_readlane_b32 s2, v251, 52
	v_fma_f32 v39, -v36, v37, 1.0
	v_fmac_f32_e32 v37, v39, v37
	v_mul_f32_e32 v39, v38, v37
	v_fma_f32 v40, -v36, v39, v38
	v_fmac_f32_e32 v39, v40, v37
	v_fma_f32 v36, -v36, v39, v38
	v_div_fmas_f32 v36, v36, v37, v39
	v_div_fixup_f32 v2, v36, v2, 1.0
	v_lshlrev_b64 v[36:37], 11, v[92:93]
	v_readlane_b32 s3, v251, 53
	v_pk_mul_f32 v[4:5], v[4:5], v[2:3] op_sel_hi:[1,0]
	v_pk_mul_f32 v[6:7], v[6:7], v[2:3] op_sel_hi:[1,0]
	v_pk_mul_f32 v[8:9], v[8:9], v[2:3] op_sel_hi:[1,0]
	v_pk_mul_f32 v[10:11], v[10:11], v[2:3] op_sel_hi:[1,0]
	v_pk_mul_f32 v[12:13], v[12:13], v[2:3] op_sel_hi:[1,0]
	v_pk_mul_f32 v[14:15], v[14:15], v[2:3] op_sel_hi:[1,0]
	v_pk_mul_f32 v[16:17], v[16:17], v[2:3] op_sel_hi:[1,0]
	v_pk_mul_f32 v[18:19], v[18:19], v[2:3] op_sel_hi:[1,0]
	v_pk_mul_f32 v[20:21], v[20:21], v[2:3] op_sel_hi:[1,0]
	v_pk_mul_f32 v[22:23], v[22:23], v[2:3] op_sel_hi:[1,0]
	v_pk_mul_f32 v[24:25], v[24:25], v[2:3] op_sel_hi:[1,0]
	v_pk_mul_f32 v[26:27], v[26:27], v[2:3] op_sel_hi:[1,0]
	v_pk_mul_f32 v[28:29], v[28:29], v[2:3] op_sel_hi:[1,0]
	v_pk_mul_f32 v[30:31], v[30:31], v[2:3] op_sel_hi:[1,0]
	v_pk_mul_f32 v[32:33], v[32:33], v[2:3] op_sel_hi:[1,0]
	v_pk_mul_f32 v[34:35], v[34:35], v[2:3] op_sel_hi:[1,0]
	v_lshl_add_u64 v[36:37], s[2:3], 0, v[36:37]
	v_cvt_pk_bf16_f32 v40, v20, v21
	v_cvt_pk_bf16_f32 v41, v22, v23
	v_cvt_pk_bf16_f32 v42, v24, v25
	v_cvt_pk_bf16_f32 v43, v26, v27
	v_cvt_pk_bf16_f32 v44, v28, v29
	v_cvt_pk_bf16_f32 v45, v30, v31
	v_cvt_pk_bf16_f32 v46, v32, v33
	v_cvt_pk_bf16_f32 v47, v34, v35
	v_cvt_pk_bf16_f32 v48, v4, v5
	v_cvt_pk_bf16_f32 v49, v6, v7
	v_cvt_pk_bf16_f32 v50, v8, v9
	v_cvt_pk_bf16_f32 v51, v10, v11
	v_cvt_pk_bf16_f32 v52, v12, v13
	v_cvt_pk_bf16_f32 v53, v14, v15
	v_cvt_pk_bf16_f32 v54, v16, v17
	v_cvt_pk_bf16_f32 v55, v18, v19
	v_lshl_add_u64 v[36:37], v[98:99], 1, v[36:37]
	s_nop 1
	v_permlane32_swap_b32 v40, v42
	v_permlane32_swap_b32 v41, v43
	v_permlane32_swap_b32 v44, v46
	v_permlane32_swap_b32 v45, v47
	v_permlane32_swap_b32 v48, v50
	v_permlane32_swap_b32 v49, v51
	v_permlane32_swap_b32 v52, v54
	v_permlane32_swap_b32 v53, v55
	s_nop 1
	s_cmp_lg_u32 s101, 0
	s_cbranch_scc1 .Lst_wt_96
	global_store_dwordx4 v[36:37], v[40:43], off
	global_store_dwordx4 v[36:37], v[44:47], off offset:32
	global_store_dwordx4 v[36:37], v[48:51], off offset:64
	global_store_dwordx4 v[36:37], v[52:55], off offset:96
	s_branch .Lst_done_96
.Lst_wt_96:
	global_store_dwordx4 v[36:37], v[40:43], off sc1
	global_store_dwordx4 v[36:37], v[44:47], off offset:32 sc1
	global_store_dwordx4 v[36:37], v[48:51], off offset:64 sc1
	global_store_dwordx4 v[36:37], v[52:55], off offset:96 sc1
.Lst_done_96:
	s_barrier
.LBB0_387:
	s_and_b64 vcc, exec, s[28:29]
	s_cbranch_vccz .LBB0_310
	v_mov_b32_e32 v8, v0
	s_movk_i32 s0, 0x1d1
	v_and_b32_e32 v4, 0x1ff, v8
	v_cmp_gt_u32_e32 vcc, s0, v4
	v_readfirstlane_b32 s49, v4
	s_and_b64 s[4:5], s[46:47], vcc
	s_and_saveexec_b64 s[2:3], s[4:5]
	s_cbranch_execz .LBB0_390
	v_lshlrev_b32_e32 v2, 2, v4
	global_load_dword v5, v2, s[22:23]
	v_or_b32_e32 v2, 0x18000, v2
	s_waitcnt vmcnt(0)
	v_mul_f32_e32 v5, 0x3fb8aa3b, v5
	ds_write_b32 v2, v5
